# k9 plus accumulator zeroing with 64 v_mov_b64 instead of 128 v_mov_b32 per tile
# baseline (speedup 1.0000x reference)
; template <class Epi, class Sched, bool ALIGN_EPI = false, bool SP2 = false>
; __device__ __forceinline__ void gemm_phase(PG8_LAS unsigned char* lds, const Gemm g, const Sched& S, const Epi& E, const int wv0) {
;     ...
;         if (!has_next) break;
;         if constexpr (!epi_keeps_acc<Epi>::value) {
; #pragma unroll
;         for (int a = 0; a < 2; ++a)
; #pragma unroll
;             for (int b = 0; b < 2; ++b)
; #pragma unroll
;                 for (int m = 0; m < 4; ++m)
; #pragma unroll
;                     for (int n = 0; n < 2; ++n) acc[a][b][m][n] = (f32x4){0.f, 0.f, 0.f, 0.f};
;         }
;         cur = nxt; cA = nA; cB = nB; ++ui;
.LBB0_81:
	s_add_u32 s21, s34, 0x100
	s_addc_u32 s23, s35, 0
	s_add_u32 s30, s30, 0x80080
	v_mov_b64_e32 v[0:1], 0
	v_mov_b64_e32 v[2:3], 0
	v_mov_b64_e32 v[4:5], 0
	v_mov_b64_e32 v[6:7], 0
	v_mov_b64_e32 v[8:9], 0
	v_mov_b64_e32 v[10:11], 0
	v_mov_b64_e32 v[12:13], 0
	v_mov_b64_e32 v[14:15], 0
	v_mov_b64_e32 v[16:17], 0
	v_mov_b64_e32 v[18:19], 0
	v_mov_b64_e32 v[20:21], 0
	v_mov_b64_e32 v[22:23], 0
	v_mov_b64_e32 v[24:25], 0
	v_mov_b64_e32 v[26:27], 0
	v_mov_b64_e32 v[28:29], 0
	v_mov_b64_e32 v[30:31], 0
	v_mov_b64_e32 v[32:33], 0
	v_mov_b64_e32 v[34:35], 0
	v_mov_b64_e32 v[36:37], 0
	v_mov_b64_e32 v[38:39], 0
	v_mov_b64_e32 v[40:41], 0
	v_mov_b64_e32 v[42:43], 0
	v_mov_b64_e32 v[44:45], 0
	v_mov_b64_e32 v[46:47], 0
	v_mov_b64_e32 v[48:49], 0
	v_mov_b64_e32 v[50:51], 0
	v_mov_b64_e32 v[52:53], 0
	v_mov_b64_e32 v[54:55], 0
	v_mov_b64_e32 v[56:57], 0
	v_mov_b64_e32 v[58:59], 0
	v_mov_b64_e32 v[60:61], 0
	v_mov_b64_e32 v[62:63], 0
	v_mov_b64_e32 v[64:65], 0
	v_mov_b64_e32 v[66:67], 0
	v_mov_b64_e32 v[68:69], 0
	v_mov_b64_e32 v[70:71], 0
	v_mov_b64_e32 v[72:73], 0
	v_mov_b64_e32 v[74:75], 0
	v_mov_b64_e32 v[76:77], 0
	v_mov_b64_e32 v[78:79], 0
	v_mov_b64_e32 v[80:81], 0
	v_mov_b64_e32 v[82:83], 0
	v_mov_b64_e32 v[84:85], 0
	v_mov_b64_e32 v[86:87], 0
	v_mov_b64_e32 v[88:89], 0
	v_mov_b64_e32 v[90:91], 0
	v_mov_b64_e32 v[92:93], 0
	v_mov_b64_e32 v[94:95], 0
	v_mov_b64_e32 v[96:97], 0
	v_mov_b64_e32 v[98:99], 0
	v_mov_b64_e32 v[100:101], 0
	v_mov_b64_e32 v[102:103], 0
	v_mov_b64_e32 v[104:105], 0
	v_mov_b64_e32 v[106:107], 0
	v_mov_b64_e32 v[108:109], 0
	v_mov_b64_e32 v[110:111], 0
	v_mov_b64_e32 v[112:113], 0
	v_mov_b64_e32 v[114:115], 0
	v_mov_b64_e32 v[116:117], 0
	v_mov_b64_e32 v[118:119], 0
	v_mov_b64_e32 v[120:121], 0
	v_mov_b64_e32 v[122:123], 0
	v_mov_b64_e32 v[124:125], 0
	v_mov_b64_e32 v[126:127], 0
	s_addc_u32 s31, s31, 0
	s_mov_b32 s38, -2

; template <class Epi, class Sched, bool ALIGN_EPI = false, bool SP2 = false>
; __device__ __forceinline__ void gemm_phase(PG8_LAS unsigned char* lds, const Gemm g, const Sched& S, const Epi& E, const int wv0) {
;     ...
;         if (!has_next) break;
;         if constexpr (!epi_keeps_acc<Epi>::value) {
; #pragma unroll
;         for (int a = 0; a < 2; ++a)
; #pragma unroll
;             for (int b = 0; b < 2; ++b)
; #pragma unroll
;                 for (int m = 0; m < 4; ++m)
; #pragma unroll
;                     for (int n = 0; n < 2; ++n) acc[a][b][m][n] = (f32x4){0.f, 0.f, 0.f, 0.f};
;         }
;         cur = nxt; cA = nA; cB = nB; ++ui;
.LBB0_666:
	s_add_u32 s13, s24, 0x100
	s_addc_u32 s15, s25, 0
	s_add_u32 s22, s22, 0x80080
	v_mov_b64_e32 v[0:1], 0
	v_mov_b64_e32 v[2:3], 0
	v_mov_b64_e32 v[4:5], 0
	v_mov_b64_e32 v[6:7], 0
	v_mov_b64_e32 v[8:9], 0
	v_mov_b64_e32 v[10:11], 0
	v_mov_b64_e32 v[12:13], 0
	v_mov_b64_e32 v[14:15], 0
	v_mov_b64_e32 v[16:17], 0
	v_mov_b64_e32 v[18:19], 0
	v_mov_b64_e32 v[20:21], 0
	v_mov_b64_e32 v[22:23], 0
	v_mov_b64_e32 v[24:25], 0
	v_mov_b64_e32 v[26:27], 0
	v_mov_b64_e32 v[28:29], 0
	v_mov_b64_e32 v[30:31], 0
	v_mov_b64_e32 v[32:33], 0
	v_mov_b64_e32 v[34:35], 0
	v_mov_b64_e32 v[36:37], 0
	v_mov_b64_e32 v[38:39], 0
	v_mov_b64_e32 v[40:41], 0
	v_mov_b64_e32 v[42:43], 0
	v_mov_b64_e32 v[44:45], 0
	v_mov_b64_e32 v[46:47], 0
	v_mov_b64_e32 v[48:49], 0
	v_mov_b64_e32 v[50:51], 0
	v_mov_b64_e32 v[52:53], 0
	v_mov_b64_e32 v[54:55], 0
	v_mov_b64_e32 v[56:57], 0
	v_mov_b64_e32 v[58:59], 0
	v_mov_b64_e32 v[60:61], 0
	v_mov_b64_e32 v[62:63], 0
	v_mov_b64_e32 v[64:65], 0
	v_mov_b64_e32 v[66:67], 0
	v_mov_b64_e32 v[68:69], 0
	v_mov_b64_e32 v[70:71], 0
	v_mov_b64_e32 v[72:73], 0
	v_mov_b64_e32 v[74:75], 0
	v_mov_b64_e32 v[76:77], 0
	v_mov_b64_e32 v[78:79], 0
	v_mov_b64_e32 v[80:81], 0
	v_mov_b64_e32 v[82:83], 0
	v_mov_b64_e32 v[84:85], 0
	v_mov_b64_e32 v[86:87], 0
	v_mov_b64_e32 v[88:89], 0
	v_mov_b64_e32 v[90:91], 0
	v_mov_b64_e32 v[92:93], 0
	v_mov_b64_e32 v[94:95], 0
	v_mov_b64_e32 v[96:97], 0
	v_mov_b64_e32 v[98:99], 0
	v_mov_b64_e32 v[100:101], 0
	v_mov_b64_e32 v[102:103], 0
	v_mov_b64_e32 v[104:105], 0
	v_mov_b64_e32 v[106:107], 0
	v_mov_b64_e32 v[108:109], 0
	v_mov_b64_e32 v[110:111], 0
	v_mov_b64_e32 v[112:113], 0
	v_mov_b64_e32 v[114:115], 0
	v_mov_b64_e32 v[116:117], 0
	v_mov_b64_e32 v[118:119], 0
	v_mov_b64_e32 v[120:121], 0
	v_mov_b64_e32 v[122:123], 0
	v_mov_b64_e32 v[124:125], 0
	v_mov_b64_e32 v[126:127], 0
	s_addc_u32 s23, s23, 0
	s_mov_b32 s50, -2

; template <class Epi, class Sched, bool ALIGN_EPI = false, bool SP2 = false>
; __device__ __forceinline__ void gemm_phase(PG8_LAS unsigned char* lds, const Gemm g, const Sched& S, const Epi& E, const int wv0) {
;     ...
;         if (!has_next) break;
;         if constexpr (!epi_keeps_acc<Epi>::value) {
; #pragma unroll
;         for (int a = 0; a < 2; ++a)
; #pragma unroll
;             for (int b = 0; b < 2; ++b)
; #pragma unroll
;                 for (int m = 0; m < 4; ++m)
; #pragma unroll
;                     for (int n = 0; n < 2; ++n) acc[a][b][m][n] = (f32x4){0.f, 0.f, 0.f, 0.f};
;         }
;         cur = nxt; cA = nA; cB = nB; ++ui;
.LBB0_789:
	s_add_u32 s11, s22, 0x100
	s_addc_u32 s13, s23, 0
	s_add_u32 s20, s20, 0x80080
	v_mov_b64_e32 v[0:1], 0
	v_mov_b64_e32 v[2:3], 0
	v_mov_b64_e32 v[4:5], 0
	v_mov_b64_e32 v[6:7], 0
	v_mov_b64_e32 v[8:9], 0
	v_mov_b64_e32 v[10:11], 0
	v_mov_b64_e32 v[12:13], 0
	v_mov_b64_e32 v[14:15], 0
	v_mov_b64_e32 v[16:17], 0
	v_mov_b64_e32 v[18:19], 0
	v_mov_b64_e32 v[20:21], 0
	v_mov_b64_e32 v[22:23], 0
	v_mov_b64_e32 v[24:25], 0
	v_mov_b64_e32 v[26:27], 0
	v_mov_b64_e32 v[28:29], 0
	v_mov_b64_e32 v[30:31], 0
	v_mov_b64_e32 v[32:33], 0
	v_mov_b64_e32 v[34:35], 0
	v_mov_b64_e32 v[36:37], 0
	v_mov_b64_e32 v[38:39], 0
	v_mov_b64_e32 v[40:41], 0
	v_mov_b64_e32 v[42:43], 0
	v_mov_b64_e32 v[44:45], 0
	v_mov_b64_e32 v[46:47], 0
	v_mov_b64_e32 v[48:49], 0
	v_mov_b64_e32 v[50:51], 0
	v_mov_b64_e32 v[52:53], 0
	v_mov_b64_e32 v[54:55], 0
	v_mov_b64_e32 v[56:57], 0
	v_mov_b64_e32 v[58:59], 0
	v_mov_b64_e32 v[60:61], 0
	v_mov_b64_e32 v[62:63], 0
	v_mov_b64_e32 v[64:65], 0
	v_mov_b64_e32 v[66:67], 0
	v_mov_b64_e32 v[68:69], 0
	v_mov_b64_e32 v[70:71], 0
	v_mov_b64_e32 v[72:73], 0
	v_mov_b64_e32 v[74:75], 0
	v_mov_b64_e32 v[76:77], 0
	v_mov_b64_e32 v[78:79], 0
	v_mov_b64_e32 v[80:81], 0
	v_mov_b64_e32 v[82:83], 0
	v_mov_b64_e32 v[84:85], 0
	v_mov_b64_e32 v[86:87], 0
	v_mov_b64_e32 v[88:89], 0
	v_mov_b64_e32 v[90:91], 0
	v_mov_b64_e32 v[92:93], 0
	v_mov_b64_e32 v[94:95], 0
	v_mov_b64_e32 v[96:97], 0
	v_mov_b64_e32 v[98:99], 0
	v_mov_b64_e32 v[100:101], 0
	v_mov_b64_e32 v[102:103], 0
	v_mov_b64_e32 v[104:105], 0
	v_mov_b64_e32 v[106:107], 0
	v_mov_b64_e32 v[108:109], 0
	v_mov_b64_e32 v[110:111], 0
	v_mov_b64_e32 v[112:113], 0
	v_mov_b64_e32 v[114:115], 0
	v_mov_b64_e32 v[116:117], 0
	v_mov_b64_e32 v[118:119], 0
	v_mov_b64_e32 v[120:121], 0
	v_mov_b64_e32 v[122:123], 0
	v_mov_b64_e32 v[124:125], 0
	v_mov_b64_e32 v[126:127], 0
	s_addc_u32 s21, s21, 0
	s_mov_b32 s50, -2

; template <class Epi, class Sched, bool ALIGN_EPI = false, bool SP2 = false>
; __device__ __forceinline__ void gemm_phase(PG8_LAS unsigned char* lds, const Gemm g, const Sched& S, const Epi& E, const int wv0) {
;     ...
;         if (!has_next) break;
;         if constexpr (!epi_keeps_acc<Epi>::value) {
; #pragma unroll
;         for (int a = 0; a < 2; ++a)
; #pragma unroll
;             for (int b = 0; b < 2; ++b)
; #pragma unroll
;                 for (int m = 0; m < 4; ++m)
; #pragma unroll
;                     for (int n = 0; n < 2; ++n) acc[a][b][m][n] = (f32x4){0.f, 0.f, 0.f, 0.f};
;         }
;         cur = nxt; cA = nA; cB = nB; ++ui;
.LBB0_866:
	s_add_u32 s56, s24, 0x100
	v_mov_b64_e32 v[0:1], 0
	v_mov_b64_e32 v[2:3], 0
	v_mov_b64_e32 v[4:5], 0
	v_mov_b64_e32 v[6:7], 0
	v_mov_b64_e32 v[8:9], 0
	v_mov_b64_e32 v[10:11], 0
	v_mov_b64_e32 v[12:13], 0
	v_mov_b64_e32 v[14:15], 0
	v_mov_b64_e32 v[16:17], 0
	v_mov_b64_e32 v[18:19], 0
	v_mov_b64_e32 v[20:21], 0
	v_mov_b64_e32 v[22:23], 0
	v_mov_b64_e32 v[24:25], 0
	v_mov_b64_e32 v[26:27], 0
	v_mov_b64_e32 v[28:29], 0
	v_mov_b64_e32 v[30:31], 0
	v_mov_b64_e32 v[32:33], 0
	v_mov_b64_e32 v[34:35], 0
	v_mov_b64_e32 v[36:37], 0
	v_mov_b64_e32 v[38:39], 0
	v_mov_b64_e32 v[40:41], 0
	v_mov_b64_e32 v[42:43], 0
	v_mov_b64_e32 v[44:45], 0
	v_mov_b64_e32 v[46:47], 0
	v_mov_b64_e32 v[48:49], 0
	v_mov_b64_e32 v[50:51], 0
	v_mov_b64_e32 v[52:53], 0
	v_mov_b64_e32 v[54:55], 0
	v_mov_b64_e32 v[56:57], 0
	v_mov_b64_e32 v[58:59], 0
	v_mov_b64_e32 v[60:61], 0
	v_mov_b64_e32 v[62:63], 0
	v_mov_b64_e32 v[64:65], 0
	v_mov_b64_e32 v[66:67], 0
	v_mov_b64_e32 v[68:69], 0
	v_mov_b64_e32 v[70:71], 0
	v_mov_b64_e32 v[72:73], 0
	v_mov_b64_e32 v[74:75], 0
	v_mov_b64_e32 v[76:77], 0
	v_mov_b64_e32 v[78:79], 0
	v_mov_b64_e32 v[80:81], 0
	v_mov_b64_e32 v[82:83], 0
	v_mov_b64_e32 v[84:85], 0
	v_mov_b64_e32 v[86:87], 0
	v_mov_b64_e32 v[88:89], 0
	v_mov_b64_e32 v[90:91], 0
	v_mov_b64_e32 v[92:93], 0
	v_mov_b64_e32 v[94:95], 0
	v_mov_b64_e32 v[96:97], 0
	v_mov_b64_e32 v[98:99], 0
	v_mov_b64_e32 v[100:101], 0
	v_mov_b64_e32 v[102:103], 0
	v_mov_b64_e32 v[104:105], 0
	v_mov_b64_e32 v[106:107], 0
	v_mov_b64_e32 v[108:109], 0
	v_mov_b64_e32 v[110:111], 0
	v_mov_b64_e32 v[112:113], 0
	v_mov_b64_e32 v[114:115], 0
	v_mov_b64_e32 v[116:117], 0
	v_mov_b64_e32 v[118:119], 0
	v_mov_b64_e32 v[120:121], 0
	v_mov_b64_e32 v[122:123], 0
	v_mov_b64_e32 v[124:125], 0
	v_mov_b64_e32 v[126:127], 0
	s_addc_u32 s57, s25, 0
	s_mov_b32 s58, -2

; template <class Epi, class Sched, bool ALIGN_EPI = false, bool SP2 = false>
; __device__ __forceinline__ void gemm_phase(PG8_LAS unsigned char* lds, const Gemm g, const Sched& S, const Epi& E, const int wv0) {
;     ...
;         if (!has_next) break;
;         if constexpr (!epi_keeps_acc<Epi>::value) {
; #pragma unroll
;         for (int a = 0; a < 2; ++a)
; #pragma unroll
;             for (int b = 0; b < 2; ++b)
; #pragma unroll
;                 for (int m = 0; m < 4; ++m)
; #pragma unroll
;                     for (int n = 0; n < 2; ++n) acc[a][b][m][n] = (f32x4){0.f, 0.f, 0.f, 0.f};
;         }
;         cur = nxt; cA = nA; cB = nB; ++ui;
.LBB0_1607:
	s_add_u32 s19, s30, 0x100
	s_addc_u32 s21, s31, 0
	s_add_u32 s28, s28, 0x80080
	v_mov_b64_e32 v[0:1], 0
	v_mov_b64_e32 v[2:3], 0
	v_mov_b64_e32 v[4:5], 0
	v_mov_b64_e32 v[6:7], 0
	v_mov_b64_e32 v[8:9], 0
	v_mov_b64_e32 v[10:11], 0
	v_mov_b64_e32 v[12:13], 0
	v_mov_b64_e32 v[14:15], 0
	v_mov_b64_e32 v[16:17], 0
	v_mov_b64_e32 v[18:19], 0
	v_mov_b64_e32 v[20:21], 0
	v_mov_b64_e32 v[22:23], 0
	v_mov_b64_e32 v[24:25], 0
	v_mov_b64_e32 v[26:27], 0
	v_mov_b64_e32 v[28:29], 0
	v_mov_b64_e32 v[30:31], 0
	v_mov_b64_e32 v[32:33], 0
	v_mov_b64_e32 v[34:35], 0
	v_mov_b64_e32 v[36:37], 0
	v_mov_b64_e32 v[38:39], 0
	v_mov_b64_e32 v[40:41], 0
	v_mov_b64_e32 v[42:43], 0
	v_mov_b64_e32 v[44:45], 0
	v_mov_b64_e32 v[46:47], 0
	v_mov_b64_e32 v[48:49], 0
	v_mov_b64_e32 v[50:51], 0
	v_mov_b64_e32 v[52:53], 0
	v_mov_b64_e32 v[54:55], 0
	v_mov_b64_e32 v[56:57], 0
	v_mov_b64_e32 v[58:59], 0
	v_mov_b64_e32 v[60:61], 0
	v_mov_b64_e32 v[62:63], 0
	v_mov_b64_e32 v[64:65], 0
	v_mov_b64_e32 v[66:67], 0
	v_mov_b64_e32 v[68:69], 0
	v_mov_b64_e32 v[70:71], 0
	v_mov_b64_e32 v[72:73], 0
	v_mov_b64_e32 v[74:75], 0
	v_mov_b64_e32 v[76:77], 0
	v_mov_b64_e32 v[78:79], 0
	v_mov_b64_e32 v[80:81], 0
	v_mov_b64_e32 v[82:83], 0
	v_mov_b64_e32 v[84:85], 0
	v_mov_b64_e32 v[86:87], 0
	v_mov_b64_e32 v[88:89], 0
	v_mov_b64_e32 v[90:91], 0
	v_mov_b64_e32 v[92:93], 0
	v_mov_b64_e32 v[94:95], 0
	v_mov_b64_e32 v[96:97], 0
	v_mov_b64_e32 v[98:99], 0
	v_mov_b64_e32 v[100:101], 0
	v_mov_b64_e32 v[102:103], 0
	v_mov_b64_e32 v[104:105], 0
	v_mov_b64_e32 v[106:107], 0
	v_mov_b64_e32 v[108:109], 0
	v_mov_b64_e32 v[110:111], 0
	v_mov_b64_e32 v[112:113], 0
	v_mov_b64_e32 v[114:115], 0
	v_mov_b64_e32 v[116:117], 0
	v_mov_b64_e32 v[118:119], 0
	v_mov_b64_e32 v[120:121], 0
	v_mov_b64_e32 v[122:123], 0
	v_mov_b64_e32 v[124:125], 0
	v_mov_b64_e32 v[126:127], 0
	s_addc_u32 s29, s29, 0
	s_mov_b32 s56, -2

; template <class Epi, class Sched, bool ALIGN_EPI = false, bool SP2 = false>
; __device__ __forceinline__ void gemm_phase(PG8_LAS unsigned char* lds, const Gemm g, const Sched& S, const Epi& E, const int wv0) {
;     ...
;         if (!has_next) break;
;         if constexpr (!epi_keeps_acc<Epi>::value) {
; #pragma unroll
;         for (int a = 0; a < 2; ++a)
; #pragma unroll
;             for (int b = 0; b < 2; ++b)
; #pragma unroll
;                 for (int m = 0; m < 4; ++m)
; #pragma unroll
;                     for (int n = 0; n < 2; ++n) acc[a][b][m][n] = (f32x4){0.f, 0.f, 0.f, 0.f};
;         }
;         cur = nxt; cA = nA; cB = nB; ++ui;
.LBB0_1807:
	s_add_u32 s46, s18, 0x100
	v_mov_b64_e32 v[0:1], 0
	v_mov_b64_e32 v[2:3], 0
	v_mov_b64_e32 v[4:5], 0
	v_mov_b64_e32 v[6:7], 0
	v_mov_b64_e32 v[8:9], 0
	v_mov_b64_e32 v[10:11], 0
	v_mov_b64_e32 v[12:13], 0
	v_mov_b64_e32 v[14:15], 0
	v_mov_b64_e32 v[16:17], 0
	v_mov_b64_e32 v[18:19], 0
	v_mov_b64_e32 v[20:21], 0
	v_mov_b64_e32 v[22:23], 0
	v_mov_b64_e32 v[24:25], 0
	v_mov_b64_e32 v[26:27], 0
	v_mov_b64_e32 v[28:29], 0
	v_mov_b64_e32 v[30:31], 0
	v_mov_b64_e32 v[32:33], 0
	v_mov_b64_e32 v[34:35], 0
	v_mov_b64_e32 v[36:37], 0
	v_mov_b64_e32 v[38:39], 0
	v_mov_b64_e32 v[40:41], 0
	v_mov_b64_e32 v[42:43], 0
	v_mov_b64_e32 v[44:45], 0
	v_mov_b64_e32 v[46:47], 0
	v_mov_b64_e32 v[48:49], 0
	v_mov_b64_e32 v[50:51], 0
	v_mov_b64_e32 v[52:53], 0
	v_mov_b64_e32 v[54:55], 0
	v_mov_b64_e32 v[56:57], 0
	v_mov_b64_e32 v[58:59], 0
	v_mov_b64_e32 v[60:61], 0
	v_mov_b64_e32 v[62:63], 0
	v_mov_b64_e32 v[64:65], 0
	v_mov_b64_e32 v[66:67], 0
	v_mov_b64_e32 v[68:69], 0
	v_mov_b64_e32 v[70:71], 0
	v_mov_b64_e32 v[72:73], 0
	v_mov_b64_e32 v[74:75], 0
	v_mov_b64_e32 v[76:77], 0
	v_mov_b64_e32 v[78:79], 0
	v_mov_b64_e32 v[80:81], 0
	v_mov_b64_e32 v[82:83], 0
	v_mov_b64_e32 v[84:85], 0
	v_mov_b64_e32 v[86:87], 0
	v_mov_b64_e32 v[88:89], 0
	v_mov_b64_e32 v[90:91], 0
	v_mov_b64_e32 v[92:93], 0
	v_mov_b64_e32 v[94:95], 0
	v_mov_b64_e32 v[96:97], 0
	v_mov_b64_e32 v[98:99], 0
	v_mov_b64_e32 v[100:101], 0
	v_mov_b64_e32 v[102:103], 0
	v_mov_b64_e32 v[104:105], 0
	v_mov_b64_e32 v[106:107], 0
	v_mov_b64_e32 v[108:109], 0
	v_mov_b64_e32 v[110:111], 0
	v_mov_b64_e32 v[112:113], 0
	v_mov_b64_e32 v[114:115], 0
	v_mov_b64_e32 v[116:117], 0
	v_mov_b64_e32 v[118:119], 0
	v_mov_b64_e32 v[120:121], 0
	v_mov_b64_e32 v[122:123], 0
	v_mov_b64_e32 v[124:125], 0
	v_mov_b64_e32 v[126:127], 0
	s_addc_u32 s47, s19, 0
	s_mov_b32 s48, -2
